# grid barrier: the XCD leader bumps XGEN (releases its XCD's waiters) before its own acquire invalidate, and no longer waits for the TOPGEN add to be acknowledged first
# baseline (speedup 1.0000x reference)
.LBB0_109:
	s_or_b64 exec, exec, s[8:9]
	s_mov_b64 s[8:9], exec
	v_mbcnt_lo_u32_b32 v1, s8, 0
	v_mbcnt_hi_u32_b32 v1, s9, v1
	v_cmp_eq_u32_e32 vcc, 0, v1
	s_and_saveexec_b64 s[10:11], vcc
	s_cbranch_execz .LBB0_111
	s_bcnt1_i32_b64 s3, s[8:9]
	v_mov_b32_e32 v1, 0x2000
	v_mov_b32_e32 v2, s3
	global_atomic_add v1, v2, s[6:7] offset:1024
.LBB0_111:
	s_or_b64 exec, exec, s[10:11]
	buffer_inv sc1
	s_waitcnt vmcnt(0)

.LBB0_165:
	s_or_b64 exec, exec, s[18:19]
	s_mov_b64 s[18:19], exec
	v_mbcnt_lo_u32_b32 v2, s18, 0
	v_mbcnt_hi_u32_b32 v2, s19, v2
	v_cmp_eq_u32_e32 vcc, 0, v2
	s_and_saveexec_b64 s[20:21], vcc
	s_cbranch_execz .LBB0_167
	s_bcnt1_i32_b64 s3, s[18:19]
	v_readlane_b32 s14, v255, 42
	v_mov_b32_e32 v2, s3
	v_readlane_b32 s15, v255, 43
	s_nop 4
	global_atomic_add v147, v2, s[14:15]
.LBB0_167:
	s_or_b64 exec, exec, s[20:21]
	buffer_inv sc1
	s_waitcnt vmcnt(0)
